# v25: v23 + nt cache policy on the 128 f32 weight loads of the P0 transposition loop (read-once streaming)
# speedup vs baseline: 1.0095x; 1.0095x over previous
; #define LAS __attribute__((address_space(3)))
; __host__ __device__ __forceinline__ int fsig(int p) { return (p & 1) ? ((p == 1) ? 32 : 64 - (p >> 1)) : (p >> 1); }
; template <bool PERMK = false>
; __device__ __forceinline__ void p0_transpose_item(const float* W, int K, int N, bf16* WT, int nblk, LAS float* scr, int item, int lane) {
;     const int kb = item / nblk, nb = item % nblk, k0 = 64 * kb, n0 = 32 * nb;
;     float tv[32];
; #pragma unroll
;     for (int i = 0; i < 32; ++i) { int kr = k0 + 2 * i + (lane >> 5); if (PERMK && kr >= 768) kr = (kr & ~63) + fsig(kr & 63); tv[i] = W[(size_t)kr * N + n0 + (lane & 31)]; }
; __device__ __forceinline__ void p0_prologue(const Args& a, LAS unsigned char* lds, int bid, int G, int tid) {
;     ...
;     for (int it = gw; it < 2 * PER; it += NGW) {
;         const int l = it / PER; int r = it % PER;
;         const float* win = a.in[7] + (size_t)l * 1024 * 1536; bf16* wtin = (bf16*)(ws + WS_WIN) + (size_t)l * NIN * 1024;
;         if (r < 640) { p0_transpose_item(win, 1024, 1536, wtin, 40, scr, r, lane); continue; } r -= 640;
;         if (r < 256) { p0_fold_item(win, wtin, scr, r, lane); continue; } r -= 256;
;         if (r < 512) { p0_transpose_item<true>(a.in[13] + (size_t)l * 1024 * 1024, 1024, 1024, (bf16*)(ws + WS_WOUT) + (size_t)l * 1024 * 1024, 32, scr, r, lane); continue; } r -= 512;
;         if (r < 2048) { p0_transpose_item(a.in[16] + (size_t)l * 1024 * 4096, 1024, 4096, (bf16*)(ws + WS_WFF1) + (size_t)l * 4096 * 1024, 128, scr, r, lane); continue; } r -= 2048;
;         p0_transpose_item(a.in[17] + (size_t)l * 4096 * 1024, 4096, 1024, (bf16*)(ws + WS_WFF2) + (size_t)l * 1024 * 4096, 32, scr, r, lane);
.LBB0_45:
	s_mov_b32 s0, 0x2fa0be83
	v_mul_hi_i32 v6, v1, s0
	v_lshrrev_b32_e32 v11, 31, v6
	v_ashrrev_i32_e32 v6, 10, v6
	v_add_u32_e32 v16, v6, v11
	v_mul_i32_i24_e32 v6, 0x1580, v16
	v_mul_hi_i32_i24_e32 v13, 0x600000, v16
	v_mul_i32_i24_e32 v12, 0x600000, v16
	v_sub_u32_e32 v6, v1, v6
	v_lshl_add_u64 v[14:15], s[30:31], 0, v[12:13]
	v_mul_hi_i32_i24_e32 v13, 0x300000, v16
	v_mul_i32_i24_e32 v12, 0x300000, v16
	s_movk_i32 s0, 0x27f
	v_lshl_add_u64 v[12:13], s[60:61], 0, v[12:13]
	v_cmp_lt_i32_e32 vcc, s0, v6
	s_and_saveexec_b64 s[0:1], vcc
	s_xor_b64 s[22:23], exec, s[0:1]
	s_cbranch_execz .LBB0_65
	s_movk_i32 s0, 0x37f
	v_cmp_lt_u32_e32 vcc, s0, v6
	s_and_saveexec_b64 s[0:1], vcc
	s_xor_b64 s[0:1], exec, s[0:1]
	s_cbranch_execz .LBB0_56
	s_movk_i32 s24, 0x57f
	v_ashrrev_i32_e32 v17, 31, v16
	v_cmp_lt_u32_e32 vcc, s24, v6
	s_and_saveexec_b64 s[24:25], vcc
	s_xor_b64 s[24:25], exec, s[24:25]
	s_cbranch_execz .LBB0_53
	s_movk_i32 s26, 0xd7f
	v_cmp_lt_u32_e32 vcc, s26, v6
	v_lshlrev_b64 v[14:15], 24, v[16:17]
	v_lshlrev_b64 v[12:13], 23, v[16:17]
	v_lshlrev_b32_e32 v11, 5, v6
	s_and_saveexec_b64 s[26:27], vcc
	s_xor_b64 s[26:27], exec, s[26:27]
	s_cbranch_execz .LBB0_50
	v_readlane_b32 s72, v252, 0
	v_readlane_b32 s74, v252, 2
	v_readlane_b32 s75, v252, 3
	v_lshl_add_u32 v6, v6, 1, v61
	v_and_b32_e32 v11, 0x3e0, v11
	v_lshl_add_u64 v[14:15], s[74:75], 0, v[14:15]
	v_and_b32_e32 v78, 0x1ffc0, v6
	v_lshlrev_b32_e32 v6, 2, v11
	v_or_b32_e32 v16, v78, v3
	v_lshl_add_u64 v[14:15], v[14:15], 0, v[6:7]
	v_lshlrev_b32_e32 v6, 2, v4
	v_lshl_add_u64 v[14:15], v[14:15], 0, v[6:7]
	v_lshlrev_b32_e32 v6, 12, v16
	v_lshl_add_u64 v[14:15], v[14:15], 0, v[6:7]
	s_movk_i32 s72, 0x2000
	v_add_co_u32_e32 v16, vcc, s72, v14
	s_movk_i32 s72, 0x4000
	s_nop 0
	v_addc_co_u32_e32 v17, vcc, 0, v15, vcc
	v_add_co_u32_e32 v64, vcc, s72, v14
	s_mov_b32 s72, 0xa000
	s_nop 0
	v_addc_co_u32_e32 v65, vcc, 0, v15, vcc
	v_add_co_u32_e32 v66, vcc, s19, v14
	v_lshl_add_u64 v[12:13], s[6:7], 0, v[12:13]
	s_nop 0
	v_addc_co_u32_e32 v67, vcc, 0, v15, vcc
	v_add_co_u32_e32 v68, vcc, s34, v14
	v_readlane_b32 s73, v252, 1
	s_nop 0
	v_addc_co_u32_e32 v69, vcc, 0, v15, vcc
	v_add_co_u32_e32 v70, vcc, s72, v14
	s_mov_b32 s72, 0xe000
	s_nop 0
	v_addc_co_u32_e32 v71, vcc, 0, v15, vcc
	v_add_co_u32_e32 v72, vcc, s35, v14
	v_readlane_b32 s76, v252, 4
	s_nop 0
	v_addc_co_u32_e32 v73, vcc, 0, v15, vcc
	v_add_co_u32_e32 v74, vcc, s72, v14
	s_mov_b32 s72, 0x14000
	s_nop 0
	v_addc_co_u32_e32 v75, vcc, 0, v15, vcc
	global_load_dword v6, v[14:15], off nt
	global_load_dword v79, v[16:17], off nt
	global_load_dword v80, v[64:65], off nt
	global_load_dword v81, v[66:67], off nt
	global_load_dword v82, v[68:69], off nt
	global_load_dword v83, v[70:71], off nt
	global_load_dword v84, v[72:73], off nt
	global_load_dword v85, v[74:75], off nt
	v_add_co_u32_e32 v16, vcc, s36, v14
	v_readlane_b32 s77, v252, 5
	s_nop 0
	v_addc_co_u32_e32 v17, vcc, 0, v15, vcc
	v_add_co_u32_e32 v64, vcc, s37, v14
	v_readlane_b32 s78, v252, 6
	s_nop 0
	v_addc_co_u32_e32 v65, vcc, 0, v15, vcc
	v_add_co_u32_e32 v66, vcc, s72, v14
	s_mov_b32 s72, 0x16000
	s_nop 0
	v_addc_co_u32_e32 v67, vcc, 0, v15, vcc
	v_add_co_u32_e32 v68, vcc, s72, v14
	s_mov_b32 s72, 0x1a000
	s_nop 0
	v_addc_co_u32_e32 v69, vcc, 0, v15, vcc
	v_add_co_u32_e32 v70, vcc, s38, v14
	v_readlane_b32 s79, v252, 7
	s_nop 0
	v_addc_co_u32_e32 v71, vcc, 0, v15, vcc
	v_add_co_u32_e32 v72, vcc, s72, v14
	s_mov_b32 s72, 0x1c000
	s_nop 0
	v_addc_co_u32_e32 v73, vcc, 0, v15, vcc
	v_add_co_u32_e32 v74, vcc, s72, v14
	s_mov_b32 s72, 0x22000
	s_nop 0
	v_addc_co_u32_e32 v75, vcc, 0, v15, vcc
	v_add_co_u32_e32 v76, vcc, s39, v14
	s_nop 1
	v_addc_co_u32_e32 v77, vcc, 0, v15, vcc
	global_load_dword v86, v[16:17], off nt
	global_load_dword v87, v[64:65], off nt
	global_load_dword v88, v[66:67], off nt
	global_load_dword v89, v[68:69], off nt
	global_load_dword v90, v[70:71], off nt
	global_load_dword v91, v[72:73], off nt
	global_load_dword v92, v[74:75], off nt
	global_load_dword v93, v[76:77], off nt
	v_add_co_u32_e32 v16, vcc, s40, v14
	s_nop 1
	v_addc_co_u32_e32 v17, vcc, 0, v15, vcc
	v_add_co_u32_e32 v64, vcc, s72, v14
	s_mov_b32 s72, 0x26000
	s_nop 0
	v_addc_co_u32_e32 v65, vcc, 0, v15, vcc
	v_add_co_u32_e32 v66, vcc, s41, v14
	s_nop 1
	v_addc_co_u32_e32 v67, vcc, 0, v15, vcc
	v_add_co_u32_e32 v68, vcc, s72, v14
	s_mov_b32 s72, 0x2c000
	s_nop 0
	v_addc_co_u32_e32 v69, vcc, 0, v15, vcc
	v_add_co_u32_e32 v70, vcc, s42, v14
	s_nop 1
	v_addc_co_u32_e32 v71, vcc, 0, v15, vcc
	v_add_co_u32_e32 v72, vcc, s43, v14
	s_nop 1
	v_addc_co_u32_e32 v73, vcc, 0, v15, vcc
	v_add_co_u32_e32 v74, vcc, s72, v14
	s_mov_b32 s72, 0x2e000
	s_nop 0
	v_addc_co_u32_e32 v75, vcc, 0, v15, vcc
	v_add_co_u32_e32 v76, vcc, s72, v14
	s_mov_b32 s72, 0x32000
	s_nop 0
	v_addc_co_u32_e32 v77, vcc, 0, v15, vcc
	global_load_dword v94, v[16:17], off nt
	global_load_dword v95, v[64:65], off nt
	global_load_dword v96, v[66:67], off nt
	global_load_dword v97, v[68:69], off nt
	global_load_dword v98, v[70:71], off nt
	global_load_dword v99, v[72:73], off nt
	global_load_dword v100, v[74:75], off nt
	s_nop 0
	global_load_dword v76, v[76:77], off nt
	v_add_co_u32_e32 v16, vcc, s44, v14
	s_nop 1
	v_addc_co_u32_e32 v17, vcc, 0, v15, vcc
	v_add_co_u32_e32 v64, vcc, s72, v14
	s_mov_b32 s72, 0x34000
	s_nop 0
	v_addc_co_u32_e32 v65, vcc, 0, v15, vcc
	v_add_co_u32_e32 v66, vcc, s72, v14
	s_mov_b32 s72, 0x3a000
	s_nop 0
	v_addc_co_u32_e32 v67, vcc, 0, v15, vcc
	v_add_co_u32_e32 v68, vcc, s45, v14
	s_nop 1
	v_addc_co_u32_e32 v69, vcc, 0, v15, vcc
	v_add_co_u32_e32 v70, vcc, s46, v14
	s_nop 1
	v_addc_co_u32_e32 v71, vcc, 0, v15, vcc
	v_add_co_u32_e32 v72, vcc, s72, v14
	s_mov_b32 s72, 0x3e000
	s_nop 0
	v_addc_co_u32_e32 v73, vcc, 0, v15, vcc
	v_add_co_u32_e32 v74, vcc, s47, v14
	s_nop 1
	v_addc_co_u32_e32 v75, vcc, 0, v15, vcc
	v_add_co_u32_e32 v14, vcc, s72, v14
	s_nop 1
	v_addc_co_u32_e32 v15, vcc, 0, v15, vcc
	global_load_dword v16, v[16:17], off nt
	s_nop 0
	global_load_dword v17, v[64:65], off nt
	s_nop 0
	global_load_dword v64, v[66:67], off nt
	global_load_dword v65, v[68:69], off nt
	s_nop 0
	global_load_dword v66, v[70:71], off nt
	global_load_dword v67, v[72:73], off nt
	global_load_dword v68, v[74:75], off nt
	s_nop 0
	global_load_dword v14, v[14:15], off nt
	s_waitcnt vmcnt(30)
; __device__ __forceinline__ unsigned cvt_pk_bf16(float lo, float hi) { unsigned r; asm volatile("v_cvt_pk_bf16_f32 %0, %1, %2" : "=v"(r) : "v"(lo), "v"(hi)); return r; }
; #define LAS __attribute__((address_space(3)))
; #define LDS_WAIT() asm volatile("s_waitcnt lgkmcnt(0)" ::: "memory")
; __host__ __device__ __forceinline__ int fsig(int p) { return (p & 1) ? ((p == 1) ? 32 : 64 - (p >> 1)) : (p >> 1); }
; template <bool PERMK = false>
; __device__ __forceinline__ void p0_transpose_item(const float* W, int K, int N, bf16* WT, int nblk, LAS float* scr, int item, int lane) {
;     const int kb = item / nblk, nb = item % nblk, k0 = 64 * kb, n0 = 32 * nb;
;     float tv[32];
; #pragma unroll
;     for (int i = 0; i < 32; ++i) { int kr = k0 + 2 * i + (lane >> 5); if (PERMK && kr >= 768) kr = (kr & ~63) + fsig(kr & 63); tv[i] = W[(size_t)kr * N + n0 + (lane & 31)]; }
; #pragma unroll
;     for (int i = 0; i < 32; ++i) scr[(2 * i + (lane >> 5)) * 33 + (lane & 31)] = tv[i];
;     LDS_WAIT();
;     const int c = lane & 7;
; #pragma unroll
;     for (int j = 0; j < 4; ++j) { const int n = (lane >> 3) + 8 * j; const LAS float* s = scr + (8 * c) * 33 + n;
;         v4u o; o.x = cvt_pk_bf16(s[0 * 33], s[1 * 33]); o.y = cvt_pk_bf16(s[2 * 33], s[3 * 33]); o.z = cvt_pk_bf16(s[4 * 33], s[5 * 33]); o.w = cvt_pk_bf16(s[6 * 33], s[7 * 33]);
;         *(v4u*)(WT + (size_t)(n0 + n) * K + k0 + 8 * c) = o; }
;     LDS_WAIT();
	ds_write2_b32 v5, v6, v79 offset1:66
	s_waitcnt vmcnt(28)
	ds_write2_b32 v5, v80, v81 offset0:132 offset1:198
	v_add_u32_e32 v6, 0x400, v5
	s_waitcnt vmcnt(26)
	ds_write2_b32 v6, v82, v83 offset0:8 offset1:74
	s_waitcnt vmcnt(24)
	ds_write2_b32 v6, v84, v85 offset0:140 offset1:206
	v_add_u32_e32 v6, 0x800, v5
	s_waitcnt vmcnt(22)
	ds_write2_b32 v6, v86, v87 offset0:16 offset1:82
	s_waitcnt vmcnt(20)
	ds_write2_b32 v6, v88, v89 offset0:148 offset1:214
	v_add_u32_e32 v6, 0xc00, v5
	s_waitcnt vmcnt(18)
	ds_write2_b32 v6, v90, v91 offset0:24 offset1:90
	s_waitcnt vmcnt(16)
	ds_write2_b32 v6, v92, v93 offset0:156 offset1:222
	v_add_u32_e32 v6, 0x1000, v5
	s_waitcnt vmcnt(14)
	ds_write2_b32 v6, v94, v95 offset0:32 offset1:98
	s_waitcnt vmcnt(12)
	ds_write2_b32 v6, v96, v97 offset0:164 offset1:230
	v_add_u32_e32 v6, 0x1400, v5
	s_waitcnt vmcnt(10)
	ds_write2_b32 v6, v98, v99 offset0:40 offset1:106
	s_waitcnt vmcnt(8)
	ds_write2_b32 v6, v100, v76 offset0:172 offset1:238
	v_add_u32_e32 v6, 0x1800, v5
	s_waitcnt vmcnt(6)
	ds_write2_b32 v6, v16, v17 offset0:48 offset1:114
	s_waitcnt vmcnt(4)
	ds_write2_b32 v6, v64, v65 offset0:180 offset1:246
	v_add_u32_e32 v6, 0x1c00, v5
	s_waitcnt vmcnt(2)
	ds_write2_b32 v6, v66, v67 offset0:56 offset1:122
	s_waitcnt vmcnt(0)
	ds_write2_b32 v6, v68, v14 offset0:188 offset1:254
	s_waitcnt lgkmcnt(0)
	ds_read2_b32 v[14:15], v18 offset1:33
	v_lshlrev_b32_e32 v6, 1, v78
	s_waitcnt lgkmcnt(0)
	v_cvt_pk_bf16_f32 v14, v14, v15
	ds_read2_b32 v[16:17], v18 offset0:66 offset1:99
	v_lshl_add_u64 v[12:13], v[12:13], 0, v[6:7]
	v_lshlrev_b32_e32 v6, 1, v8
	s_waitcnt lgkmcnt(0)
	v_cvt_pk_bf16_f32 v15, v16, v17
	ds_read2_b32 v[16:17], v18 offset0:132 offset1:165
	v_lshl_add_u64 v[66:67], v[12:13], 0, v[6:7]
	v_or_b32_e32 v6, v11, v9
	s_waitcnt lgkmcnt(0)
	v_cvt_pk_bf16_f32 v16, v16, v17
	ds_read2_b32 v[64:65], v18 offset0:198 offset1:231
	v_lshlrev_b32_e32 v6, 13, v6
	s_waitcnt lgkmcnt(0)
	v_cvt_pk_bf16_f32 v17, v64, v65
	ds_read2_b32 v[12:13], v18 offset0:8 offset1:41
	v_lshl_add_u64 v[64:65], v[66:67], 0, v[6:7]
	global_store_dwordx4 v[64:65], v[14:17], off
	s_waitcnt lgkmcnt(0)
	v_cvt_pk_bf16_f32 v12, v12, v13
	ds_read2_b32 v[14:15], v18 offset0:74 offset1:107
	v_or_b32_e32 v6, v11, v19
	s_waitcnt lgkmcnt(0)
	v_cvt_pk_bf16_f32 v13, v14, v15
	ds_read2_b32 v[14:15], v18 offset0:140 offset1:173
	v_lshlrev_b32_e32 v6, 13, v6
	s_waitcnt lgkmcnt(0)
	v_cvt_pk_bf16_f32 v14, v14, v15
	ds_read2_b32 v[16:17], v18 offset0:206 offset1:239
	s_waitcnt lgkmcnt(0)
	v_cvt_pk_bf16_f32 v15, v16, v17
	v_lshl_add_u64 v[64:65], v[66:67], 0, v[6:7]
	ds_read2_b32 v[16:17], v18 offset0:16 offset1:49
	global_store_dwordx4 v[64:65], v[12:15], off
	v_or_b32_e32 v6, v11, v20
	v_lshlrev_b32_e32 v6, 13, v6
	s_waitcnt lgkmcnt(0)
	v_cvt_pk_bf16_f32 v12, v16, v17
	ds_read2_b32 v[14:15], v18 offset0:82 offset1:115
	s_waitcnt lgkmcnt(0)
	v_cvt_pk_bf16_f32 v13, v14, v15
	ds_read2_b32 v[14:15], v18 offset0:148 offset1:181
	s_waitcnt lgkmcnt(0)
	v_cvt_pk_bf16_f32 v14, v14, v15
	ds_read2_b32 v[16:17], v18 offset0:214 offset1:247
	s_waitcnt lgkmcnt(0)
	v_cvt_pk_bf16_f32 v15, v16, v17
	v_lshl_add_u64 v[64:65], v[66:67], 0, v[6:7]
	ds_read2_b32 v[16:17], v18 offset0:24 offset1:57
	global_store_dwordx4 v[64:65], v[12:15], off
	v_or_b32_e32 v6, v11, v21
	v_lshlrev_b32_e32 v6, 13, v6
	s_waitcnt lgkmcnt(0)
	v_cvt_pk_bf16_f32 v12, v16, v17
	ds_read2_b32 v[14:15], v18 offset0:90 offset1:123
	s_waitcnt lgkmcnt(0)
	v_cvt_pk_bf16_f32 v13, v14, v15
	ds_read2_b32 v[14:15], v18 offset0:156 offset1:189
	s_waitcnt lgkmcnt(0)
	v_cvt_pk_bf16_f32 v14, v14, v15
	ds_read2_b32 v[16:17], v18 offset0:222 offset1:255
	s_waitcnt lgkmcnt(0)
	v_cvt_pk_bf16_f32 v15, v16, v17
	v_lshl_add_u64 v[16:17], v[66:67], 0, v[6:7]
	global_store_dwordx4 v[16:17], v[12:15], off
	s_waitcnt lgkmcnt(0)
.LBB0_50:
	s_andn2_saveexec_b64 s[26:27], s[26:27]
	s_cbranch_execz .LBB0_52
	v_readlane_b32 s72, v252, 0
	v_add_u32_e32 v6, 0xfa80, v6
	v_readlane_b32 s73, v252, 1
	v_lshrrev_b32_e32 v6, 1, v6
	v_and_b32_e32 v11, 0xfe0, v11
	v_lshl_add_u64 v[14:15], s[72:73], 0, v[14:15]
	v_and_b32_e32 v78, 0x7fc0, v6
	v_lshlrev_b32_e32 v6, 2, v11
	v_or_b32_e32 v16, v78, v3
	v_lshl_add_u64 v[14:15], v[14:15], 0, v[6:7]
	v_lshlrev_b32_e32 v6, 2, v4
	v_lshl_add_u64 v[14:15], v[14:15], 0, v[6:7]
	v_lshlrev_b32_e32 v6, 14, v16
	v_lshl_add_u64 v[14:15], v[14:15], 0, v[6:7]
	v_add_co_u32_e32 v16, vcc, s34, v14
	s_mov_b32 s72, 0x40000
	s_nop 0
	v_addc_co_u32_e32 v17, vcc, 0, v15, vcc
	v_add_co_u32_e32 v64, vcc, s36, v14
	v_lshl_add_u64 v[12:13], s[10:11], 0, v[12:13]
	s_nop 0
	v_addc_co_u32_e32 v65, vcc, 0, v15, vcc
	v_add_co_u32_e32 v66, vcc, s38, v14
	v_readlane_b32 s74, v252, 2
	s_nop 0
	v_addc_co_u32_e32 v67, vcc, 0, v15, vcc
	v_add_co_u32_e32 v68, vcc, s40, v14
	v_readlane_b32 s75, v252, 3
	s_nop 0
	v_addc_co_u32_e32 v69, vcc, 0, v15, vcc
	v_add_co_u32_e32 v70, vcc, s42, v14
	v_readlane_b32 s76, v252, 4
	s_nop 0
	v_addc_co_u32_e32 v71, vcc, 0, v15, vcc
	v_add_co_u32_e32 v72, vcc, s44, v14
	v_readlane_b32 s77, v252, 5
	s_nop 0
	v_addc_co_u32_e32 v73, vcc, 0, v15, vcc
	v_add_co_u32_e32 v74, vcc, s46, v14
	v_readlane_b32 s78, v252, 6
	s_nop 0
	v_addc_co_u32_e32 v75, vcc, 0, v15, vcc
	global_load_dword v6, v[14:15], off nt
	global_load_dword v79, v[16:17], off nt
	global_load_dword v80, v[64:65], off nt
	global_load_dword v81, v[66:67], off nt
	global_load_dword v82, v[68:69], off nt
	global_load_dword v83, v[70:71], off nt
	global_load_dword v84, v[72:73], off nt
	global_load_dword v85, v[74:75], off nt
	v_add_co_u32_e32 v16, vcc, s72, v14
	s_mov_b32 s72, 0x50000
	s_nop 0
	v_addc_co_u32_e32 v17, vcc, 0, v15, vcc
; #define LAS __attribute__((address_space(3)))
; __host__ __device__ __forceinline__ int fsig(int p) { return (p & 1) ? ((p == 1) ? 32 : 64 - (p >> 1)) : (p >> 1); }
; template <bool PERMK = false>
; __device__ __forceinline__ void p0_transpose_item(const float* W, int K, int N, bf16* WT, int nblk, LAS float* scr, int item, int lane) {
;     const int kb = item / nblk, nb = item % nblk, k0 = 64 * kb, n0 = 32 * nb;
;     float tv[32];
; #pragma unroll
;     for (int i = 0; i < 32; ++i) { int kr = k0 + 2 * i + (lane >> 5); if (PERMK && kr >= 768) kr = (kr & ~63) + fsig(kr & 63); tv[i] = W[(size_t)kr * N + n0 + (lane & 31)]; }
; #pragma unroll
;     for (int i = 0; i < 32; ++i) scr[(2 * i + (lane >> 5)) * 33 + (lane & 31)] = tv[i];
	v_add_co_u32_e32 v64, vcc, s48, v14
	v_readlane_b32 s79, v252, 7
	s_nop 0
	v_addc_co_u32_e32 v65, vcc, 0, v15, vcc
	v_add_co_u32_e32 v66, vcc, s72, v14
	s_mov_b32 s72, 0x58000
	s_nop 0
	v_addc_co_u32_e32 v67, vcc, 0, v15, vcc
	v_add_co_u32_e32 v68, vcc, s72, v14
	s_mov_b32 s72, 0x60000
	s_nop 0
	v_addc_co_u32_e32 v69, vcc, 0, v15, vcc
	v_add_co_u32_e32 v70, vcc, s72, v14
	s_mov_b32 s72, 0x68000
	s_nop 0
	v_addc_co_u32_e32 v71, vcc, 0, v15, vcc
	v_add_co_u32_e32 v72, vcc, s72, v14
	s_mov_b32 s72, 0x70000
	s_nop 0
	v_addc_co_u32_e32 v73, vcc, 0, v15, vcc
	v_add_co_u32_e32 v74, vcc, s72, v14
	s_mov_b32 s72, 0x78000
	s_nop 0
	v_addc_co_u32_e32 v75, vcc, 0, v15, vcc
	v_add_co_u32_e32 v76, vcc, s72, v14
	s_mov_b32 s72, 0x80000
	s_nop 0
	v_addc_co_u32_e32 v77, vcc, 0, v15, vcc
	global_load_dword v86, v[16:17], off nt
	global_load_dword v87, v[64:65], off nt
	global_load_dword v88, v[66:67], off nt
	global_load_dword v89, v[68:69], off nt
	global_load_dword v90, v[70:71], off nt
	global_load_dword v91, v[72:73], off nt
	global_load_dword v92, v[74:75], off nt
	global_load_dword v93, v[76:77], off nt
	v_add_co_u32_e32 v16, vcc, s72, v14
	s_mov_b32 s72, 0x88000
	s_nop 0
	v_addc_co_u32_e32 v17, vcc, 0, v15, vcc
	v_add_co_u32_e32 v64, vcc, s72, v14
	s_mov_b32 s72, 0x90000
	s_nop 0
	v_addc_co_u32_e32 v65, vcc, 0, v15, vcc
	v_add_co_u32_e32 v66, vcc, s72, v14
	s_mov_b32 s72, 0x98000
	s_nop 0
	v_addc_co_u32_e32 v67, vcc, 0, v15, vcc
	v_add_co_u32_e32 v68, vcc, s72, v14
	s_mov_b32 s72, 0xa0000
	s_nop 0
	v_addc_co_u32_e32 v69, vcc, 0, v15, vcc
	v_add_co_u32_e32 v70, vcc, s72, v14
	s_mov_b32 s72, 0xa8000
	s_nop 0
	v_addc_co_u32_e32 v71, vcc, 0, v15, vcc
	v_add_co_u32_e32 v72, vcc, s72, v14
	s_mov_b32 s72, 0xb0000
	s_nop 0
	v_addc_co_u32_e32 v73, vcc, 0, v15, vcc
	v_add_co_u32_e32 v74, vcc, s72, v14
	s_mov_b32 s72, 0xb8000
	s_nop 0
	v_addc_co_u32_e32 v75, vcc, 0, v15, vcc
	v_add_co_u32_e32 v76, vcc, s72, v14
	s_mov_b32 s72, 0xc0000
	s_nop 0
	v_addc_co_u32_e32 v77, vcc, 0, v15, vcc
	global_load_dword v94, v[16:17], off nt
	global_load_dword v95, v[64:65], off nt
	global_load_dword v96, v[66:67], off nt
	global_load_dword v97, v[68:69], off nt
	global_load_dword v98, v[70:71], off nt
	global_load_dword v99, v[72:73], off nt
	global_load_dword v100, v[74:75], off nt
	s_nop 0
	global_load_dword v76, v[76:77], off nt
	v_add_co_u32_e32 v16, vcc, s72, v14
	s_mov_b32 s72, 0xc8000
	s_nop 0
	v_addc_co_u32_e32 v17, vcc, 0, v15, vcc
	v_add_co_u32_e32 v64, vcc, s72, v14
	s_mov_b32 s72, 0xd0000
	s_nop 0
	v_addc_co_u32_e32 v65, vcc, 0, v15, vcc
	v_add_co_u32_e32 v66, vcc, s72, v14
	s_mov_b32 s72, 0xd8000
	s_nop 0
	v_addc_co_u32_e32 v67, vcc, 0, v15, vcc
	v_add_co_u32_e32 v68, vcc, s72, v14
	s_mov_b32 s72, 0xe0000
	s_nop 0
	v_addc_co_u32_e32 v69, vcc, 0, v15, vcc
	v_add_co_u32_e32 v70, vcc, s72, v14
	s_mov_b32 s72, 0xe8000
	s_nop 0
	v_addc_co_u32_e32 v71, vcc, 0, v15, vcc
	v_add_co_u32_e32 v72, vcc, s72, v14
	s_mov_b32 s72, 0xf0000
	s_nop 0
	v_addc_co_u32_e32 v73, vcc, 0, v15, vcc
	v_add_co_u32_e32 v74, vcc, s72, v14
	s_mov_b32 s72, 0xf8000
	s_nop 0
	v_addc_co_u32_e32 v75, vcc, 0, v15, vcc
	v_add_co_u32_e32 v14, vcc, s72, v14
	s_nop 1
	v_addc_co_u32_e32 v15, vcc, 0, v15, vcc
	global_load_dword v16, v[16:17], off nt
	s_nop 0
	global_load_dword v17, v[64:65], off nt
	s_nop 0
	global_load_dword v64, v[66:67], off nt
	global_load_dword v65, v[68:69], off nt
	s_nop 0
	global_load_dword v66, v[70:71], off nt
	global_load_dword v67, v[72:73], off nt
	global_load_dword v68, v[74:75], off nt
	s_nop 0
	global_load_dword v14, v[14:15], off nt
	s_waitcnt vmcnt(30)
	ds_write2_b32 v5, v6, v79 offset1:66
	s_waitcnt vmcnt(28)
; __device__ __forceinline__ unsigned cvt_pk_bf16(float lo, float hi) { unsigned r; asm volatile("v_cvt_pk_bf16_f32 %0, %1, %2" : "=v"(r) : "v"(lo), "v"(hi)); return r; }
; #define LAS __attribute__((address_space(3)))
; #define LDS_WAIT() asm volatile("s_waitcnt lgkmcnt(0)" ::: "memory")
; template <bool PERMK = false>
; __device__ __forceinline__ void p0_transpose_item(const float* W, int K, int N, bf16* WT, int nblk, LAS float* scr, int item, int lane) {
;     ...
; #pragma unroll
;     for (int i = 0; i < 32; ++i) scr[(2 * i + (lane >> 5)) * 33 + (lane & 31)] = tv[i];
;     LDS_WAIT();
;     const int c = lane & 7;
; #pragma unroll
;     for (int j = 0; j < 4; ++j) { const int n = (lane >> 3) + 8 * j; const LAS float* s = scr + (8 * c) * 33 + n;
;         v4u o; o.x = cvt_pk_bf16(s[0 * 33], s[1 * 33]); o.y = cvt_pk_bf16(s[2 * 33], s[3 * 33]); o.z = cvt_pk_bf16(s[4 * 33], s[5 * 33]); o.w = cvt_pk_bf16(s[6 * 33], s[7 * 33]);
;         *(v4u*)(WT + (size_t)(n0 + n) * K + k0 + 8 * c) = o; }
;     LDS_WAIT();
	ds_write2_b32 v5, v80, v81 offset0:132 offset1:198
	v_add_u32_e32 v6, 0x400, v5
	s_waitcnt vmcnt(26)
	ds_write2_b32 v6, v82, v83 offset0:8 offset1:74
	s_waitcnt vmcnt(24)
	ds_write2_b32 v6, v84, v85 offset0:140 offset1:206
	v_add_u32_e32 v6, 0x800, v5
	s_waitcnt vmcnt(22)
	ds_write2_b32 v6, v86, v87 offset0:16 offset1:82
	s_waitcnt vmcnt(20)
	ds_write2_b32 v6, v88, v89 offset0:148 offset1:214
	v_add_u32_e32 v6, 0xc00, v5
	s_waitcnt vmcnt(18)
	ds_write2_b32 v6, v90, v91 offset0:24 offset1:90
	s_waitcnt vmcnt(16)
	ds_write2_b32 v6, v92, v93 offset0:156 offset1:222
	v_add_u32_e32 v6, 0x1000, v5
	s_waitcnt vmcnt(14)
	ds_write2_b32 v6, v94, v95 offset0:32 offset1:98
	s_waitcnt vmcnt(12)
	ds_write2_b32 v6, v96, v97 offset0:164 offset1:230
	v_add_u32_e32 v6, 0x1400, v5
	s_waitcnt vmcnt(10)
	ds_write2_b32 v6, v98, v99 offset0:40 offset1:106
	s_waitcnt vmcnt(8)
	ds_write2_b32 v6, v100, v76 offset0:172 offset1:238
	v_add_u32_e32 v6, 0x1800, v5
	s_waitcnt vmcnt(6)
	ds_write2_b32 v6, v16, v17 offset0:48 offset1:114
	s_waitcnt vmcnt(4)
	ds_write2_b32 v6, v64, v65 offset0:180 offset1:246
	v_add_u32_e32 v6, 0x1c00, v5
	s_waitcnt vmcnt(2)
	ds_write2_b32 v6, v66, v67 offset0:56 offset1:122
	s_waitcnt vmcnt(0)
	ds_write2_b32 v6, v68, v14 offset0:188 offset1:254
	s_waitcnt lgkmcnt(0)
	ds_read2_b32 v[14:15], v18 offset1:33
	v_lshlrev_b32_e32 v6, 1, v78
	s_waitcnt lgkmcnt(0)
	v_cvt_pk_bf16_f32 v14, v14, v15
	ds_read2_b32 v[16:17], v18 offset0:66 offset1:99
	v_lshl_add_u64 v[12:13], v[12:13], 0, v[6:7]
	v_lshlrev_b32_e32 v6, 1, v8
	s_waitcnt lgkmcnt(0)
	v_cvt_pk_bf16_f32 v15, v16, v17
	ds_read2_b32 v[16:17], v18 offset0:132 offset1:165
	v_lshl_add_u64 v[66:67], v[12:13], 0, v[6:7]
	v_or_b32_e32 v6, v11, v9
	s_waitcnt lgkmcnt(0)
	v_cvt_pk_bf16_f32 v16, v16, v17
	ds_read2_b32 v[64:65], v18 offset0:198 offset1:231
	v_lshlrev_b32_e32 v6, 11, v6
	s_waitcnt lgkmcnt(0)
	v_cvt_pk_bf16_f32 v17, v64, v65
	ds_read2_b32 v[12:13], v18 offset0:8 offset1:41
	v_lshl_add_u64 v[64:65], v[66:67], 0, v[6:7]
	global_store_dwordx4 v[64:65], v[14:17], off
	s_waitcnt lgkmcnt(0)
	v_cvt_pk_bf16_f32 v12, v12, v13
	ds_read2_b32 v[14:15], v18 offset0:74 offset1:107
	v_or_b32_e32 v6, v11, v19
	s_waitcnt lgkmcnt(0)
	v_cvt_pk_bf16_f32 v13, v14, v15
	ds_read2_b32 v[14:15], v18 offset0:140 offset1:173
	v_lshlrev_b32_e32 v6, 11, v6
	s_waitcnt lgkmcnt(0)
	v_cvt_pk_bf16_f32 v14, v14, v15
	ds_read2_b32 v[16:17], v18 offset0:206 offset1:239
	s_waitcnt lgkmcnt(0)
	v_cvt_pk_bf16_f32 v15, v16, v17
	v_lshl_add_u64 v[64:65], v[66:67], 0, v[6:7]
	ds_read2_b32 v[16:17], v18 offset0:16 offset1:49
	global_store_dwordx4 v[64:65], v[12:15], off
	v_or_b32_e32 v6, v11, v20
	v_lshlrev_b32_e32 v6, 11, v6
	s_waitcnt lgkmcnt(0)
	v_cvt_pk_bf16_f32 v12, v16, v17
	ds_read2_b32 v[14:15], v18 offset0:82 offset1:115
	s_waitcnt lgkmcnt(0)
	v_cvt_pk_bf16_f32 v13, v14, v15
	ds_read2_b32 v[14:15], v18 offset0:148 offset1:181
	s_waitcnt lgkmcnt(0)
	v_cvt_pk_bf16_f32 v14, v14, v15
	ds_read2_b32 v[16:17], v18 offset0:214 offset1:247
	s_waitcnt lgkmcnt(0)
	v_cvt_pk_bf16_f32 v15, v16, v17
	v_lshl_add_u64 v[64:65], v[66:67], 0, v[6:7]
	ds_read2_b32 v[16:17], v18 offset0:24 offset1:57
	global_store_dwordx4 v[64:65], v[12:15], off
	v_or_b32_e32 v6, v11, v21
	v_lshlrev_b32_e32 v6, 11, v6
	s_waitcnt lgkmcnt(0)
	v_cvt_pk_bf16_f32 v12, v16, v17
	ds_read2_b32 v[14:15], v18 offset0:90 offset1:123
	s_waitcnt lgkmcnt(0)
	v_cvt_pk_bf16_f32 v13, v14, v15
	ds_read2_b32 v[14:15], v18 offset0:156 offset1:189
	s_waitcnt lgkmcnt(0)
	v_cvt_pk_bf16_f32 v14, v14, v15
	ds_read2_b32 v[16:17], v18 offset0:222 offset1:255
	s_waitcnt lgkmcnt(0)
	v_cvt_pk_bf16_f32 v15, v16, v17
	v_lshl_add_u64 v[16:17], v[66:67], 0, v[6:7]
	global_store_dwordx4 v[16:17], v[12:15], off
	s_waitcnt lgkmcnt(0)

; #define LAS __attribute__((address_space(3)))
; __host__ __device__ __forceinline__ int fsig(int p) { return (p & 1) ? ((p == 1) ? 32 : 64 - (p >> 1)) : (p >> 1); }
; template <bool PERMK = false>
; __device__ __forceinline__ void p0_transpose_item(const float* W, int K, int N, bf16* WT, int nblk, LAS float* scr, int item, int lane) {
;     const int kb = item / nblk, nb = item % nblk, k0 = 64 * kb, n0 = 32 * nb;
;     float tv[32];
; #pragma unroll
;     for (int i = 0; i < 32; ++i) { int kr = k0 + 2 * i + (lane >> 5); if (PERMK && kr >= 768) kr = (kr & ~63) + fsig(kr & 63); tv[i] = W[(size_t)kr * N + n0 + (lane & 31)]; }
.LBB0_53:
	s_andn2_saveexec_b64 s[24:25], s[24:25]
	s_cbranch_execz .LBB0_55
	v_add_u32_e32 v11, 0xfffffc80, v6
	v_lshlrev_b32_e32 v6, 5, v11
	v_lshlrev_b64 v[12:13], 22, v[16:17]
	v_and_b32_e32 v78, 0x3e0, v6
	s_waitcnt lgkmcnt(0)
	v_lshl_add_u64 v[12:13], s[90:91], 0, v[12:13]
	v_lshlrev_b32_e32 v6, 2, v78
	s_movk_i32 s26, 0x17f
	v_and_b32_e32 v64, 0x1e0, v11
	v_lshl_add_u64 v[12:13], v[12:13], 0, v[6:7]
	v_lshlrev_b32_e32 v6, 2, v4
	v_cmp_lt_u32_e32 vcc, s26, v11
	v_lshl_add_u64 v[12:13], v[12:13], 0, v[6:7]
	v_lshlrev_b32_e32 v14, 13, v64
	v_cndmask_b32_e32 v6, v3, v22, vcc
	v_lshlrev_b32_e32 v79, 1, v64
	v_lshl_or_b32 v6, v6, 12, v14
	v_or_b32_e32 v80, v79, v3
	v_lshl_add_u64 v[14:15], v[12:13], 0, v[6:7]
	v_or_b32_e32 v6, 2, v80
	v_or_b32_e32 v64, v79, v23
	v_cndmask_b32_e32 v6, v6, v64, vcc
	v_lshlrev_b32_e32 v6, 12, v6
	v_lshl_add_u64 v[64:65], v[12:13], 0, v[6:7]
	v_or_b32_e32 v6, 4, v80
	v_or_b32_e32 v66, v79, v24
	v_cndmask_b32_e32 v6, v6, v66, vcc
	v_lshlrev_b32_e32 v6, 12, v6
	v_lshl_add_u64 v[66:67], v[12:13], 0, v[6:7]
	v_or_b32_e32 v6, 6, v80
	v_or_b32_e32 v68, v79, v25
	v_cndmask_b32_e32 v6, v6, v68, vcc
	v_lshlrev_b32_e32 v6, 12, v6
	v_lshl_add_u64 v[68:69], v[12:13], 0, v[6:7]
	v_or_b32_e32 v6, 8, v80
	v_or_b32_e32 v70, v79, v26
	v_cndmask_b32_e32 v6, v6, v70, vcc
	v_lshlrev_b32_e32 v6, 12, v6
	v_lshl_add_u64 v[70:71], v[12:13], 0, v[6:7]
	v_or_b32_e32 v6, 10, v80
	v_or_b32_e32 v72, v79, v27
	v_cndmask_b32_e32 v6, v6, v72, vcc
	v_lshlrev_b32_e32 v6, 12, v6
	v_lshl_add_u64 v[72:73], v[12:13], 0, v[6:7]
	v_or_b32_e32 v6, 12, v80
	v_or_b32_e32 v74, v79, v28
	v_cndmask_b32_e32 v6, v6, v74, vcc
	v_lshlrev_b32_e32 v6, 12, v6
	v_lshl_add_u64 v[74:75], v[12:13], 0, v[6:7]
	v_or_b32_e32 v6, 14, v80
	v_or_b32_e32 v76, v79, v29
	v_cndmask_b32_e32 v6, v6, v76, vcc
	v_lshlrev_b32_e32 v6, 12, v6
	v_lshl_add_u64 v[76:77], v[12:13], 0, v[6:7]
	global_load_dword v81, v[14:15], off nt
	global_load_dword v82, v[64:65], off nt
	global_load_dword v83, v[66:67], off nt
	global_load_dword v84, v[68:69], off nt
	global_load_dword v85, v[70:71], off nt
	global_load_dword v86, v[72:73], off nt
	global_load_dword v87, v[74:75], off nt
	global_load_dword v88, v[76:77], off nt
	v_or_b32_e32 v6, 16, v80
	v_or_b32_e32 v14, v79, v30
	v_cndmask_b32_e32 v6, v6, v14, vcc
	v_lshlrev_b32_e32 v6, 12, v6
	v_lshl_add_u64 v[14:15], v[12:13], 0, v[6:7]
	v_or_b32_e32 v6, 18, v80
	v_or_b32_e32 v64, v79, v31
	v_cndmask_b32_e32 v6, v6, v64, vcc
	v_lshlrev_b32_e32 v6, 12, v6
	v_lshl_add_u64 v[64:65], v[12:13], 0, v[6:7]
	v_or_b32_e32 v6, 20, v80
	v_or_b32_e32 v66, v79, v32
	v_cndmask_b32_e32 v6, v6, v66, vcc
	v_lshlrev_b32_e32 v6, 12, v6
	v_lshl_add_u64 v[66:67], v[12:13], 0, v[6:7]
	v_or_b32_e32 v6, 22, v80
	v_or_b32_e32 v68, v79, v33
	v_cndmask_b32_e32 v6, v6, v68, vcc
	v_lshlrev_b32_e32 v6, 12, v6
	v_lshl_add_u64 v[68:69], v[12:13], 0, v[6:7]
	v_or_b32_e32 v6, 24, v80
	v_or_b32_e32 v70, v79, v34
	v_cndmask_b32_e32 v6, v6, v70, vcc
	v_lshlrev_b32_e32 v6, 12, v6
	v_lshl_add_u64 v[70:71], v[12:13], 0, v[6:7]
	v_or_b32_e32 v6, 26, v80
	v_or_b32_e32 v72, v79, v35
	v_cndmask_b32_e32 v6, v6, v72, vcc
	v_lshlrev_b32_e32 v6, 12, v6
	v_lshl_add_u64 v[72:73], v[12:13], 0, v[6:7]
	v_or_b32_e32 v6, 28, v80
	v_or_b32_e32 v74, v79, v36
	v_cndmask_b32_e32 v6, v6, v74, vcc
	v_lshlrev_b32_e32 v6, 12, v6
	v_lshl_add_u64 v[74:75], v[12:13], 0, v[6:7]
	v_or_b32_e32 v6, 30, v80
	v_or_b32_e32 v76, v79, v37
	v_cndmask_b32_e32 v6, v6, v76, vcc
	v_lshlrev_b32_e32 v6, 12, v6
	v_lshl_add_u64 v[76:77], v[12:13], 0, v[6:7]
	global_load_dword v89, v[14:15], off nt
	global_load_dword v90, v[64:65], off nt
	global_load_dword v91, v[66:67], off nt
	global_load_dword v92, v[68:69], off nt
	global_load_dword v93, v[70:71], off nt
	global_load_dword v94, v[72:73], off nt
	global_load_dword v95, v[74:75], off nt
	global_load_dword v96, v[76:77], off nt
	v_or_b32_e32 v6, 32, v80
	v_or_b32_e32 v14, v79, v38
	v_cndmask_b32_e32 v6, v6, v14, vcc
	v_lshlrev_b32_e32 v6, 12, v6
	v_lshl_add_u64 v[14:15], v[12:13], 0, v[6:7]
	v_or_b32_e32 v6, 34, v80
	v_or_b32_e32 v64, v79, v39
	v_cndmask_b32_e32 v6, v6, v64, vcc
	v_lshlrev_b32_e32 v6, 12, v6
	v_lshl_add_u64 v[64:65], v[12:13], 0, v[6:7]
	v_or_b32_e32 v6, 36, v80
	v_or_b32_e32 v66, v79, v40
	v_cndmask_b32_e32 v6, v6, v66, vcc
	v_lshlrev_b32_e32 v6, 12, v6
	v_lshl_add_u64 v[66:67], v[12:13], 0, v[6:7]
	v_or_b32_e32 v6, 38, v80
	v_or_b32_e32 v68, v79, v41
	v_cndmask_b32_e32 v6, v6, v68, vcc
	v_lshlrev_b32_e32 v6, 12, v6
	v_lshl_add_u64 v[68:69], v[12:13], 0, v[6:7]
	v_or_b32_e32 v6, 40, v80
	v_or_b32_e32 v70, v79, v42
	v_cndmask_b32_e32 v6, v6, v70, vcc
	v_lshlrev_b32_e32 v6, 12, v6
	v_lshl_add_u64 v[70:71], v[12:13], 0, v[6:7]
	v_or_b32_e32 v6, 42, v80
	v_or_b32_e32 v72, v79, v43
	v_cndmask_b32_e32 v6, v6, v72, vcc
	v_lshlrev_b32_e32 v6, 12, v6
	v_lshl_add_u64 v[72:73], v[12:13], 0, v[6:7]
	v_or_b32_e32 v6, 44, v80
	v_or_b32_e32 v74, v79, v44
	v_cndmask_b32_e32 v6, v6, v74, vcc
	v_lshlrev_b32_e32 v6, 12, v6
	v_lshl_add_u64 v[74:75], v[12:13], 0, v[6:7]
	v_or_b32_e32 v6, 46, v80
	v_or_b32_e32 v76, v79, v45
	v_cndmask_b32_e32 v6, v6, v76, vcc
	v_lshlrev_b32_e32 v6, 12, v6
	v_lshl_add_u64 v[76:77], v[12:13], 0, v[6:7]
	global_load_dword v97, v[14:15], off nt
	global_load_dword v98, v[64:65], off nt
	global_load_dword v99, v[66:67], off nt
	global_load_dword v100, v[68:69], off nt
	global_load_dword v101, v[70:71], off nt
	global_load_dword v102, v[72:73], off nt
	global_load_dword v103, v[74:75], off nt
	s_nop 0
	global_load_dword v76, v[76:77], off nt
	v_or_b32_e32 v6, 48, v80
	v_or_b32_e32 v14, v79, v46
; __device__ __forceinline__ unsigned cvt_pk_bf16(float lo, float hi) { unsigned r; asm volatile("v_cvt_pk_bf16_f32 %0, %1, %2" : "=v"(r) : "v"(lo), "v"(hi)); return r; }
; #define LAS __attribute__((address_space(3)))
; #define LDS_WAIT() asm volatile("s_waitcnt lgkmcnt(0)" ::: "memory")
; __host__ __device__ __forceinline__ int fsig(int p) { return (p & 1) ? ((p == 1) ? 32 : 64 - (p >> 1)) : (p >> 1); }
; template <bool PERMK = false>
; __device__ __forceinline__ void p0_transpose_item(const float* W, int K, int N, bf16* WT, int nblk, LAS float* scr, int item, int lane) {
;     const int kb = item / nblk, nb = item % nblk, k0 = 64 * kb, n0 = 32 * nb;
;     float tv[32];
; #pragma unroll
;     for (int i = 0; i < 32; ++i) { int kr = k0 + 2 * i + (lane >> 5); if (PERMK && kr >= 768) kr = (kr & ~63) + fsig(kr & 63); tv[i] = W[(size_t)kr * N + n0 + (lane & 31)]; }
; #pragma unroll
;     for (int i = 0; i < 32; ++i) scr[(2 * i + (lane >> 5)) * 33 + (lane & 31)] = tv[i];
;     LDS_WAIT();
;     const int c = lane & 7;
; #pragma unroll
;     for (int j = 0; j < 4; ++j) { const int n = (lane >> 3) + 8 * j; const LAS float* s = scr + (8 * c) * 33 + n;
;         v4u o; o.x = cvt_pk_bf16(s[0 * 33], s[1 * 33]); o.y = cvt_pk_bf16(s[2 * 33], s[3 * 33]); o.z = cvt_pk_bf16(s[4 * 33], s[5 * 33]); o.w = cvt_pk_bf16(s[6 * 33], s[7 * 33]);
;         *(v4u*)(WT + (size_t)(n0 + n) * K + k0 + 8 * c) = o; }
;     LDS_WAIT();
	v_cndmask_b32_e32 v6, v6, v14, vcc
	v_lshlrev_b32_e32 v6, 12, v6
	v_lshl_add_u64 v[14:15], v[12:13], 0, v[6:7]
	v_or_b32_e32 v6, 50, v80
	v_or_b32_e32 v64, v79, v47
	v_cndmask_b32_e32 v6, v6, v64, vcc
	v_lshlrev_b32_e32 v6, 12, v6
	v_lshl_add_u64 v[64:65], v[12:13], 0, v[6:7]
	v_or_b32_e32 v6, 52, v80
	v_or_b32_e32 v66, v79, v48
	v_cndmask_b32_e32 v6, v6, v66, vcc
	v_lshlrev_b32_e32 v6, 12, v6
	v_lshl_add_u64 v[66:67], v[12:13], 0, v[6:7]
	v_or_b32_e32 v6, 54, v80
	v_or_b32_e32 v68, v79, v49
	v_cndmask_b32_e32 v6, v6, v68, vcc
	v_lshlrev_b32_e32 v6, 12, v6
	v_lshl_add_u64 v[68:69], v[12:13], 0, v[6:7]
	v_or_b32_e32 v6, 56, v80
	v_or_b32_e32 v70, v79, v50
	v_cndmask_b32_e32 v6, v6, v70, vcc
	v_lshlrev_b32_e32 v6, 12, v6
	v_lshl_add_u64 v[70:71], v[12:13], 0, v[6:7]
	v_or_b32_e32 v6, 58, v80
	v_or_b32_e32 v72, v79, v51
	v_cndmask_b32_e32 v6, v6, v72, vcc
	v_lshlrev_b32_e32 v6, 12, v6
	v_lshl_add_u64 v[72:73], v[12:13], 0, v[6:7]
	v_or_b32_e32 v6, 60, v80
	v_or_b32_e32 v74, v79, v52
	v_cndmask_b32_e32 v6, v6, v74, vcc
	v_lshlrev_b32_e32 v6, 12, v6
	v_lshl_add_u64 v[74:75], v[12:13], 0, v[6:7]
	v_lshlrev_b32_e32 v6, 1, v11
	v_and_b32_e32 v77, 0x3c0, v6
	v_or_b32_e32 v11, v6, v60
	v_or_b32_e32 v6, v77, v53
	v_cndmask_b32_e32 v6, v11, v6, vcc
	v_lshlrev_b32_e32 v6, 12, v6
	v_lshl_add_u64 v[12:13], v[12:13], 0, v[6:7]
	global_load_dword v6, v[14:15], off nt
	global_load_dword v11, v[64:65], off nt
	s_nop 0
	global_load_dword v14, v[66:67], off nt
	global_load_dword v15, v[68:69], off nt
	global_load_dword v64, v[70:71], off nt
	global_load_dword v65, v[72:73], off nt
	s_nop 0
	global_load_dword v66, v[74:75], off nt
	s_nop 0
	global_load_dword v12, v[12:13], off nt
	v_add_u32_e32 v13, 0x400, v5
	s_waitcnt vmcnt(30)
	ds_write2_b32 v5, v81, v82 offset1:66
	s_waitcnt vmcnt(28)
	ds_write2_b32 v5, v83, v84 offset0:132 offset1:198
	s_waitcnt vmcnt(26)
	ds_write2_b32 v13, v85, v86 offset0:8 offset1:74
	s_waitcnt vmcnt(24)
	ds_write2_b32 v13, v87, v88 offset0:140 offset1:206
	v_add_u32_e32 v13, 0x800, v5
	s_waitcnt vmcnt(22)
	ds_write2_b32 v13, v89, v90 offset0:16 offset1:82
	s_waitcnt vmcnt(20)
	ds_write2_b32 v13, v91, v92 offset0:148 offset1:214
	v_add_u32_e32 v13, 0xc00, v5
	s_waitcnt vmcnt(18)
	ds_write2_b32 v13, v93, v94 offset0:24 offset1:90
	s_waitcnt vmcnt(16)
	ds_write2_b32 v13, v95, v96 offset0:156 offset1:222
	v_add_u32_e32 v13, 0x1000, v5
	s_waitcnt vmcnt(14)
	ds_write2_b32 v13, v97, v98 offset0:32 offset1:98
	s_waitcnt vmcnt(12)
	ds_write2_b32 v13, v99, v100 offset0:164 offset1:230
	v_add_u32_e32 v13, 0x1400, v5
	s_waitcnt vmcnt(10)
	ds_write2_b32 v13, v101, v102 offset0:40 offset1:106
	s_waitcnt vmcnt(8)
	ds_write2_b32 v13, v103, v76 offset0:172 offset1:238
	v_add_u32_e32 v13, 0x1800, v5
	s_waitcnt vmcnt(6)
	ds_write2_b32 v13, v6, v11 offset0:48 offset1:114
	s_waitcnt vmcnt(4)
	ds_write2_b32 v13, v14, v15 offset0:180 offset1:246
	v_add_u32_e32 v6, 0x1c00, v5
	s_waitcnt vmcnt(2)
	ds_write2_b32 v6, v64, v65 offset0:56 offset1:122
	s_waitcnt vmcnt(0)
	ds_write2_b32 v6, v66, v12 offset0:188 offset1:254
	v_lshlrev_b64 v[16:17], 21, v[16:17]
	s_waitcnt lgkmcnt(0)
	v_lshl_add_u64 v[16:17], s[12:13], 0, v[16:17]
	v_lshlrev_b32_e32 v6, 1, v77
	ds_read2_b32 v[12:13], v18 offset1:33
	v_lshl_add_u64 v[16:17], v[16:17], 0, v[6:7]
	v_lshlrev_b32_e32 v6, 1, v8
	s_waitcnt lgkmcnt(0)
	v_cvt_pk_bf16_f32 v12, v12, v13
	ds_read2_b32 v[14:15], v18 offset0:66 offset1:99
	v_lshl_add_u64 v[16:17], v[16:17], 0, v[6:7]
	v_or_b32_e32 v6, v78, v9
	s_waitcnt lgkmcnt(0)
	v_cvt_pk_bf16_f32 v13, v14, v15
	ds_read2_b32 v[14:15], v18 offset0:132 offset1:165
	v_lshlrev_b32_e32 v6, 11, v6
	s_waitcnt lgkmcnt(0)
	v_cvt_pk_bf16_f32 v14, v14, v15
	ds_read2_b32 v[64:65], v18 offset0:198 offset1:231
	s_waitcnt lgkmcnt(0)
	v_cvt_pk_bf16_f32 v15, v64, v65
	v_lshl_add_u64 v[66:67], v[16:17], 0, v[6:7]
	ds_read2_b32 v[64:65], v18 offset0:8 offset1:41
	global_store_dwordx4 v[66:67], v[12:15], off
	v_or_b32_e32 v6, v78, v19
	v_lshlrev_b32_e32 v6, 11, v6
	s_waitcnt lgkmcnt(0)
	v_cvt_pk_bf16_f32 v12, v64, v65
	ds_read2_b32 v[14:15], v18 offset0:74 offset1:107
	s_waitcnt lgkmcnt(0)
	v_cvt_pk_bf16_f32 v13, v14, v15
	ds_read2_b32 v[14:15], v18 offset0:140 offset1:173
	s_waitcnt lgkmcnt(0)
	v_cvt_pk_bf16_f32 v14, v14, v15
	ds_read2_b32 v[64:65], v18 offset0:206 offset1:239
	s_waitcnt lgkmcnt(0)
	v_cvt_pk_bf16_f32 v15, v64, v65
	v_lshl_add_u64 v[66:67], v[16:17], 0, v[6:7]
	ds_read2_b32 v[64:65], v18 offset0:16 offset1:49
	global_store_dwordx4 v[66:67], v[12:15], off
	v_or_b32_e32 v6, v78, v20
	v_lshlrev_b32_e32 v6, 11, v6
	s_waitcnt lgkmcnt(0)
	v_cvt_pk_bf16_f32 v12, v64, v65
	ds_read2_b32 v[14:15], v18 offset0:82 offset1:115
	s_waitcnt lgkmcnt(0)
	v_cvt_pk_bf16_f32 v13, v14, v15
	ds_read2_b32 v[14:15], v18 offset0:148 offset1:181
	s_waitcnt lgkmcnt(0)
	v_cvt_pk_bf16_f32 v14, v14, v15
	ds_read2_b32 v[64:65], v18 offset0:214 offset1:247
	s_waitcnt lgkmcnt(0)
	v_cvt_pk_bf16_f32 v15, v64, v65
	v_lshl_add_u64 v[66:67], v[16:17], 0, v[6:7]
	v_or_b32_e32 v6, v78, v21
	ds_read2_b32 v[64:65], v18 offset0:24 offset1:57
	global_store_dwordx4 v[66:67], v[12:15], off
	v_lshlrev_b32_e32 v6, 11, v6
	v_lshl_add_u64 v[16:17], v[16:17], 0, v[6:7]
	s_waitcnt lgkmcnt(0)
	v_cvt_pk_bf16_f32 v12, v64, v65
	ds_read2_b32 v[14:15], v18 offset0:90 offset1:123
	s_waitcnt lgkmcnt(0)
	v_cvt_pk_bf16_f32 v13, v14, v15
	ds_read2_b32 v[14:15], v18 offset0:156 offset1:189
	s_waitcnt lgkmcnt(0)
	v_cvt_pk_bf16_f32 v14, v14, v15
	ds_read2_b32 v[64:65], v18 offset0:222 offset1:255
	s_waitcnt lgkmcnt(0)
	v_cvt_pk_bf16_f32 v15, v64, v65
	global_store_dwordx4 v[16:17], v[12:15], off
	s_waitcnt lgkmcnt(0)

; #define LAS __attribute__((address_space(3)))
; #define LDS_WAIT() asm volatile("s_waitcnt lgkmcnt(0)" ::: "memory")
; __device__ __forceinline__ void p0_fold_item(const float* Win  , bf16* WT  , LAS float* scr, int item, int lane) {
;     const int g = item >> 6, k0 = ((item >> 2) & 15) * 64, q0 = (item & 3) * 16;
;     LAS float* cs = scr + 64 * 65; LAS float* sn = cs + 64;
;     cs[lane] = cospif((float)lane / 32.f); sn[lane] = -sinpif((float)lane / 32.f);
; #pragma unroll 1
;     for (int i0 = 0; i0 < 64; i0 += 32) { float tv[32];
; #pragma unroll
;         for (int i = 0; i < 32; ++i) tv[i] = Win[(size_t)(k0 + i0 + i) * 1536 + 1280 + g * 64 + lane];
; #pragma unroll
;         for (int i = 0; i < 32; ++i) scr[(i0 + i) * 65 + lane] = tv[i]; }
;     LDS_WAIT();
;     for (int q = q0; q < q0 + 16; ++q) {
.LBB0_58:
	v_or_b32_e32 v87, s26, v16
	v_mul_u32_u24_e32 v6, 0x600, v87
	v_or_b32_e32 v6, v64, v6
	v_lshl_add_u64 v[88:89], v[6:7], 2, v[14:15]
	v_add_co_u32_e32 v90, vcc, 0x1000, v88
	v_mad_u32_u24 v6, v87, s49, v75
	s_nop 0
	v_addc_co_u32_e32 v91, vcc, 0, v89, vcc
	v_add_co_u32_e32 v94, vcc, 0x2000, v88
	v_lshl_add_u64 v[92:93], v[6:7], 2, v[14:15]
	s_nop 0
	v_addc_co_u32_e32 v95, vcc, 0, v89, vcc
	v_add_co_u32_e32 v98, vcc, 0x4000, v88
	global_load_dword v110, v[90:91], off offset:1024 nt
	global_load_dword v111, v[94:95], off offset:3072 nt
	v_addc_co_u32_e32 v99, vcc, 0, v89, vcc
	v_add_co_u32_e32 v90, vcc, 0x5000, v88
	v_mad_u32_u24 v6, v87, s49, v76
	s_nop 0
	v_addc_co_u32_e32 v91, vcc, 0, v89, vcc
	v_add_co_u32_e32 v102, vcc, 0x7000, v88
	v_lshl_add_u64 v[96:97], v[6:7], 2, v[14:15]
	v_mad_u32_u24 v6, v87, s49, v77
	v_addc_co_u32_e32 v103, vcc, 0, v89, vcc
	v_lshl_add_u64 v[100:101], v[6:7], 2, v[14:15]
	v_mad_u32_u24 v6, v87, s49, v65
	global_load_dword v112, v[98:99], off offset:1024 nt
	global_load_dword v113, v[90:91], off offset:3072 nt
	v_add_co_u32_e32 v90, vcc, 0x8000, v88
	v_lshl_add_u64 v[94:95], v[6:7], 2, v[14:15]
	v_mad_u32_u24 v6, v87, s49, v66
	v_addc_co_u32_e32 v91, vcc, 0, v89, vcc
	v_lshl_add_u64 v[104:105], v[6:7], 2, v[14:15]
	v_mad_u32_u24 v6, v87, s49, v78
	v_add_co_u32_e32 v106, vcc, 0xa000, v88
	v_lshl_add_u64 v[98:99], v[6:7], 2, v[14:15]
	v_mad_u32_u24 v6, v87, s49, v79
	v_addc_co_u32_e32 v107, vcc, 0, v89, vcc
	v_lshl_add_u64 v[108:109], v[6:7], 2, v[14:15]
	v_mad_u32_u24 v6, v87, s49, v67
	global_load_dword v114, v[102:103], off offset:1024 nt
	global_load_dword v115, v[90:91], off offset:3072 nt
	v_add_co_u32_e32 v90, vcc, 0xb000, v88
	v_lshl_add_u64 v[102:103], v[6:7], 2, v[14:15]
	s_nop 0
	v_addc_co_u32_e32 v91, vcc, 0, v89, vcc
	global_load_dword v116, v[108:109], off nt
	global_load_dword v117, v[102:103], off nt
	v_mad_u32_u24 v6, v87, s49, v68
	v_add_co_u32_e32 v108, vcc, 0xd000, v88
	v_lshl_add_u64 v[102:103], v[6:7], 2, v[14:15]
	v_mad_u32_u24 v6, v87, s49, v80
	v_addc_co_u32_e32 v109, vcc, 0, v89, vcc
	global_load_dword v106, v[106:107], off offset:1024 nt
	s_nop 0
	global_load_dword v107, v[90:91], off offset:3072 nt
	v_add_co_u32_e32 v88, vcc, 0xe000, v88
	v_lshl_add_u64 v[90:91], v[6:7], 2, v[14:15]
	v_mad_u32_u24 v6, v87, s49, v81
	global_load_dword v102, v[102:103], off nt
	v_addc_co_u32_e32 v89, vcc, 0, v89, vcc
	global_load_dword v103, v[90:91], off nt
	v_lshl_add_u64 v[90:91], v[6:7], 2, v[14:15]
	v_mad_u32_u24 v6, v87, s49, v69
	global_load_dword v108, v[108:109], off offset:1024 nt
	s_nop 0
	global_load_dword v109, v[88:89], off offset:3072 nt
	s_nop 0
	global_load_dword v92, v[92:93], off nt
	s_nop 0
	global_load_dword v93, v[96:97], off nt
	s_nop 0
	global_load_dword v96, v[100:101], off nt
	s_nop 0
	global_load_dword v94, v[94:95], off nt
	s_nop 0
	global_load_dword v95, v[104:105], off nt
	global_load_dword v97, v[98:99], off nt
	v_lshl_add_u64 v[88:89], v[6:7], 2, v[14:15]
	v_mad_u32_u24 v6, v87, s49, v70
	global_load_dword v98, v[90:91], off nt
	global_load_dword v99, v[88:89], off nt
	v_lshl_add_u64 v[88:89], v[6:7], 2, v[14:15]
	v_mad_u32_u24 v6, v87, s49, v82
	v_lshl_add_u64 v[90:91], v[6:7], 2, v[14:15]
	v_mad_u32_u24 v6, v87, s49, v83
	global_load_dword v100, v[88:89], off nt
	global_load_dword v101, v[90:91], off nt
	v_lshl_add_u64 v[88:89], v[6:7], 2, v[14:15]
	v_mad_u32_u24 v6, v87, s49, v71
	v_lshl_add_u64 v[90:91], v[6:7], 2, v[14:15]
	v_mad_u32_u24 v6, v87, s49, v72
	global_load_dword v104, v[88:89], off nt
	global_load_dword v105, v[90:91], off nt
	v_lshl_add_u64 v[88:89], v[6:7], 2, v[14:15]
	v_mad_u32_u24 v6, v87, s49, v84
	v_lshl_add_u64 v[90:91], v[6:7], 2, v[14:15]
	v_mad_u32_u24 v6, v87, s49, v85
	global_load_dword v118, v[88:89], off nt
	global_load_dword v119, v[90:91], off nt
	v_lshl_add_u64 v[88:89], v[6:7], 2, v[14:15]
	v_mad_u32_u24 v6, v87, s49, v73
	v_lshl_add_u64 v[90:91], v[6:7], 2, v[14:15]
	v_mad_u32_u24 v6, v87, s49, v74
	global_load_dword v120, v[88:89], off nt
	global_load_dword v121, v[90:91], off nt
	v_lshl_add_u64 v[88:89], v[6:7], 2, v[14:15]
	v_mad_u32_u24 v6, v87, s49, v86
	v_lshl_add_u64 v[90:91], v[6:7], 2, v[14:15]
	global_load_dword v6, v[88:89], off nt
	global_load_dword v87, v[90:91], off nt
	s_mul_i32 s27, s26, 0x104
	s_mov_b32 s26, 32
	s_and_b64 vcc, exec, s[0:1]
	s_mov_b64 s[0:1], 0
	v_add_u32_e32 v88, s27, v57
	v_add_u32_e32 v89, 0x400, v88
	v_add_u32_e32 v90, 0x800, v88
	v_add_u32_e32 v91, 0xc00, v88
	v_add_u32_e32 v122, 0x1000, v88
	v_add_u32_e32 v123, 0x1400, v88
	v_add_u32_e32 v124, 0x1800, v88
	v_add_u32_e32 v125, 0x1c00, v88
	s_waitcnt vmcnt(30)
	ds_write2_b32 v88, v110, v111 offset1:65
	s_waitcnt vmcnt(28)
	ds_write2_b32 v88, v112, v113 offset0:130 offset1:195
	s_waitcnt vmcnt(26)
	ds_write2_b32 v89, v114, v115 offset0:4 offset1:69
	s_waitcnt vmcnt(24)
	ds_write2_b32 v122, v116, v117 offset0:16 offset1:81
	s_waitcnt vmcnt(22)
	ds_write2_b32 v89, v106, v107 offset0:134 offset1:199
	s_waitcnt vmcnt(20)
	ds_write2_b32 v122, v102, v103 offset0:146 offset1:211
	s_waitcnt vmcnt(18)
	ds_write2_b32 v90, v108, v109 offset0:8 offset1:73
	s_waitcnt vmcnt(16)
	ds_write2_b32 v90, v92, v93 offset0:138 offset1:203
	s_waitcnt vmcnt(14)
	ds_write2_b32 v91, v96, v94 offset0:12 offset1:77
	s_waitcnt vmcnt(12)
	ds_write2_b32 v91, v95, v97 offset0:142 offset1:207
	s_waitcnt vmcnt(10)
	ds_write2_b32 v123, v98, v99 offset0:20 offset1:85
	s_waitcnt vmcnt(8)
	ds_write2_b32 v123, v100, v101 offset0:150 offset1:215
	s_waitcnt vmcnt(6)
	ds_write2_b32 v124, v104, v105 offset0:24 offset1:89
	s_waitcnt vmcnt(4)
	ds_write2_b32 v124, v118, v119 offset0:154 offset1:219
	s_waitcnt vmcnt(2)
	ds_write2_b32 v125, v120, v121 offset0:28 offset1:93
	s_waitcnt vmcnt(0)
	ds_write2_b32 v125, v6, v87 offset0:158 offset1:223
	s_cbranch_vccnz .LBB0_58
	s_waitcnt lgkmcnt(0)
	v_lshlrev_b32_e32 v6, 1, v16
	v_and_b32_e32 v15, 48, v17
	v_or_b32_e32 v14, 0x500, v11
	v_lshl_add_u64 v[12:13], v[12:13], 0, v[6:7]
	v_mov_b32_e32 v11, v7
	v_lshl_add_u64 v[12:13], v[12:13], 0, v[10:11]
	v_or_b32_e32 v11, 15, v15
	s_mov_b64 s[26:27], 0
